# one static s_setprio 1 for waves 4-7 at the FoX attention item loop (doc 7.4 younger-half raise)
# speedup vs baseline: 1.0045x; 1.0045x over previous
; template <int CLS>
; __device__ __forceinline__ void run_phase(const Params& P, int l, int kind_in, const int wid) {
;     ...
;             for (int it = blockIdx.x; it < 512; it += gridDim.x) {
;               int bh = it & 63, gsel = it >> 6;
;               int G = gsel < 4 ? 7 - gsel : gsel - 4;
;               int b = bh >> 3, h = bh & 7;
;               int q0 = (G * 8 + (gsel < 4 ? wid : 7 - wid)) * 64;
;     ...
;               attn_wave<true>(Z + (size_t)b * 4096 * 1536 + 1024 + h * 64, 1536, kpe + (size_t)bh * 64 * 4096, 0,
;                               vt + (size_t)bh * 64 * 4096, c2 + (size_t)bh * 4096, 0.f, q0,
;                               bufY + (size_t)b * 4096 * 1024 + 512 + h * 64, 1024);
;     ...
;             }
.LBB0_506:
	v_readlane_b32 s2, v251, 18
	s_cmp_ge_u32 s2, 4
	s_cbranch_scc0 .Lfox_noprio
	s_setprio 1
